# v30 + P2: first rotary-table loads issued at the loop top alongside the Z-row loads; a_k norm gain loaded once before the token loop
# speedup vs baseline: 1.0201x; 1.0077x over previous
.LBB0_643:
	global_load_dwordx4 v[62:65], v[84:85], off
	global_load_dwordx4 v[58:61], v[84:85], off offset:64
	global_load_dwordx4 v[54:57], v[84:85], off offset:128
	global_load_dwordx4 v[50:53], v[84:85], off offset:192
	global_load_dwordx4 v[46:49], v[86:87], off
	global_load_dwordx4 v[42:45], v[88:89], off
	global_load_dwordx4 v[38:41], v[90:91], off
	global_load_dwordx4 v[34:37], v[92:93], off
	global_load_dwordx4 v[30:33], v[94:95], off
	global_load_dwordx4 v[26:29], v[96:97], off
	global_load_dwordx4 v[22:25], v[98:99], off
	global_load_dwordx4 v[18:21], v[100:101], off
	global_load_dwordx4 v[14:17], v[102:103], off
	global_load_dwordx4 v[10:13], v[104:105], off
	global_load_dwordx4 v[6:9], v[106:107], off
	global_load_dwordx4 v[2:5], v[108:109], off
	s_lshl_b32 s15, s86, 6
	s_cmpk_lt_i32 s86, 0x80
	s_cselect_b64 s[16:17], -1, 0
	s_cmpk_gt_i32 s86, 0x7f
	s_cselect_b64 s[12:13], -1, 0
	s_and_b64 s[0:1], s[12:13], exec
	s_movk_i32 s0, 0x3c0
	s_cselect_b32 s0, s0, 0xc0
	s_add_i32 s1, s15, 0xffffe000
	s_ashr_i32 s14, s86, 2
	s_and_b32 s59, s0, s15
	s_lshr_b32 s2, s1, 10
	s_and_saveexec_b64 s[18:19], s[38:39]
	s_cbranch_execz .LBB0_682
	v_ashrrev_i32_e32 v113, 31, v112
	s_movk_i32 s8, 0x300
	v_cmp_lt_i32_e32 vcc, v227, v226
	v_mad_i64_i32 v[124:125], s[0:1], v112, s95, 0
	v_mad_i64_i32 v[126:127], s[0:1], v112, s8, v[120:121]
	v_mad_i64_i32 v[128:129], s[0:1], v112, s8, v[110:111]
	v_lshlrev_b64 v[66:67], 8, v[112:113]
	s_and_b64 s[0:1], s[12:13], exec
	v_cndmask_b32_e32 v0, v224, v227, vcc
	v_cmp_lt_i32_e32 vcc, v228, v226
	v_lshl_add_u64 v[132:133], v[122:123], 0, v[66:67]
	s_cselect_b32 s0, s2, s14
	v_cndmask_b32_e32 v66, v224, v228, vcc
	v_cmp_lt_i32_e32 vcc, v229, v226
	v_lshlrev_b64 v[130:131], 9, v[112:113]
	s_lshl_b32 s0, s0, 2
	v_readlane_b32 s4, v255, 20
	v_lshlrev_b32_e32 v113, 2, v66
	v_cndmask_b32_e32 v66, v224, v229, vcc
	v_cmp_lt_i32_e32 vcc, v230, v226
	s_add_i32 s0, s0, s4
	v_lshlrev_b32_e32 v169, 2, v66
	v_cndmask_b32_e32 v66, v224, v230, vcc
	v_cmp_lt_i32_e32 vcc, v231, v226
	s_ashr_i32 s1, s0, 31
	v_lshlrev_b32_e32 v170, 2, v66
	v_cndmask_b32_e32 v66, v224, v231, vcc
	v_cmp_lt_i32_e32 vcc, v232, v226
	v_add_u32_e32 v68, s59, v115
	v_lshlrev_b32_e32 v171, 2, v66
	v_cndmask_b32_e32 v66, v224, v232, vcc
	s_lshl_b64 s[8:9], s[0:1], 17
	v_ashrrev_i32_e32 v69, 31, v68
	v_lshlrev_b32_e32 v172, 2, v66
	v_mov_b32_e32 v67, s9
	v_or_b32_e32 v66, s8, v114
	v_lshlrev_b64 v[70:71], 9, v[68:69]
	v_lshl_add_u64 v[134:135], v[66:67], 0, v[70:71]
	v_lshl_add_u64 v[66:67], v[116:117], 0, s[8:9]
	s_lshl_b64 s[8:9], s[0:1], 15
	v_lshl_add_u64 v[136:137], v[66:67], 0, v[70:71]
	v_lshl_add_u64 v[66:67], v[118:119], 0, s[8:9]
	v_lshlrev_b64 v[70:71], 7, v[68:69]
	s_lshl_b64 s[0:1], s[0:1], 18
	v_lshl_add_u64 v[138:139], v[66:67], 0, v[70:71]
	v_mov_b32_e32 v67, s1
	v_or_b32_e32 v66, s0, v114
	v_lshlrev_b64 v[68:69], 10, v[68:69]
	v_or_b32_e32 v124, v110, v124
	v_or_b32_e32 v130, v110, v130
	v_lshlrev_b32_e32 v0, 2, v0
	s_and_b64 s[68:69], s[12:13], s[76:77]
	s_and_b64 s[70:71], s[12:13], s[62:63]
	v_lshl_add_u64 v[140:141], v[66:67], 0, v[68:69]
	s_mov_b64 s[10:11], 0
	v_mov_b32_e32 v173, v167
	v_mov_b32_e32 v174, v166
	v_mov_b32_e32 v175, v165
	v_readlane_b32 s5, v255, 21
	global_load_dwordx4 v[206:209], v[78:79], off
	s_branch .LBB0_646

.LBB0_646:
	v_lshl_add_u64 v[66:67], s[24:25], 0, v[124:125]
	global_load_dwordx2 v[154:155], v[66:67], off
	global_load_dwordx4 v[70:73], v[76:77], off
	global_load_dwordx2 v[68:69], v[66:67], off offset:512
	global_load_dwordx2 v[156:157], v[66:67], off offset:2560
	global_load_dwordx2 v[152:153], v[66:67], off offset:3072
	s_movk_i32 s0, 0x1000
	v_add_co_u32_e32 v142, vcc, s0, v66
	v_add_u32_e32 v173, 8, v173
	s_nop 0
	v_addc_co_u32_e32 v143, vcc, 0, v67, vcc
	global_load_dwordx2 v[150:151], v[66:67], off offset:3584
	global_load_dwordx2 v[146:147], v[142:143], off
	s_waitcnt lgkmcnt(0)
	global_load_dwordx2 v[148:149], v[142:143], off offset:512
	global_load_dwordx2 v[144:145], v[142:143], off offset:1024
	s_nop 0
	global_load_dwordx2 v[142:143], v[142:143], off offset:1536
	v_add_u32_e32 v180, s59, v173
	v_and_b32_e32 v214, 63, v173
	v_ashrrev_i32_e32 v215, 6, v180
	v_cndmask_b32_e64 v216, v214, v215, s[40:41]
	v_cndmask_b32_e64 v217, v214, v215, s[42:43]
	v_readlane_b32 s0, v250, 10
	v_readlane_b32 s1, v250, 11
	v_lshl_or_b32 v214, v216, 5, v159
	v_ashrrev_i32_e32 v215, 31, v214
	s_nop 0
	v_lshl_add_u64 v[214:215], v[214:215], 2, s[0:1]
	global_load_dwordx4 v[194:197], v[214:215], off offset:16
	global_load_dwordx4 v[190:193], v[214:215], off
	v_readlane_b32 s0, v251, 13
	v_readlane_b32 s1, v251, 14
	v_lshl_or_b32 v216, v217, 4, v160
	v_ashrrev_i32_e32 v217, 31, v216
	s_nop 0
	v_lshl_add_u64 v[216:217], v[216:217], 2, s[0:1]
	global_load_dwordx4 v[202:205], v[216:217], off offset:16
	global_load_dwordx4 v[198:201], v[216:217], off
	s_andn2_b64 vcc, exec, s[12:13]
	s_waitcnt vmcnt(0)
	v_lshlrev_b32_e32 v66, 16, v154
	v_and_b32_e32 v67, 0xffff0000, v154
	v_lshlrev_b32_e32 v154, 16, v155
	v_and_b32_e32 v155, 0xffff0000, v155
	v_pk_mul_f32 v[176:177], v[66:67], v[66:67]
	v_pk_mul_f32 v[178:179], v[154:155], v[154:155]
	v_add_f32_e32 v176, v176, v177
	v_add_f32_e32 v176, v178, v176
	v_add_f32_e32 v176, v179, v176
	s_nop 1
	v_mov_b32_dpp v177, v176 quad_perm:[1,0,3,2] row_mask:0xf bank_mask:0xf
	v_cndmask_b32_e64 v179, 0, 1, s[12:13]
	v_cmp_ne_u32_e64 s[72:73], 1, v179
	s_waitcnt lgkmcnt(0)
	v_add_f32_e32 v176, v176, v177
	s_nop 1
	v_mov_b32_dpp v177, v176 quad_perm:[2,3,0,1] row_mask:0xf bank_mask:0xf
	s_waitcnt lgkmcnt(0)
	v_add_f32_e32 v176, v176, v177
	s_nop 1
	v_mov_b32_dpp v177, v176 row_shl:4 row_mask:0xf bank_mask:0x5
	v_mov_b32_dpp v177, v176 row_shr:4 row_mask:0xf bank_mask:0xa
	s_waitcnt lgkmcnt(0)
	v_add_f32_e32 v177, v176, v177
	s_nop 1
	v_mov_b32_dpp v178, v177 row_ror:8 row_mask:0xf bank_mask:0xf
	v_and_b32_e32 v176, 63, v173
	s_waitcnt lgkmcnt(0)
	v_add_f32_e32 v177, v177, v178
	v_fmamk_f32 v177, v177, 0x3c800000, v219
	v_mul_f32_e32 v178, 0x4b800000, v177
	v_cmp_gt_f32_e64 s[0:1], s33, v177
	s_nop 1
	v_cndmask_b32_e64 v177, v177, v178, s[0:1]
	v_rsq_f32_e32 v178, v177
	v_ashrrev_i32_e32 v177, 6, v180
	v_mul_f32_e32 v179, 0x45800000, v178
	v_cndmask_b32_e64 v178, v178, v179, s[0:1]
	v_pk_mul_f32 v[70:71], v[70:71], v[178:179] op_sel_hi:[1,0]
	v_pk_mul_f32 v[72:73], v[72:73], v[178:179] op_sel_hi:[1,0]
	v_pk_mul_f32 v[70:71], v[70:71], v[66:67]
	v_pk_mul_f32 v[66:67], v[72:73], v[154:155]
	v_cndmask_b32_e64 v178, v176, v177, s[40:41]
	s_cbranch_vccnz .LBB0_648
	v_lshl_or_b32 v154, v178, 5, v159
	v_readlane_b32 s0, v250, 10
	v_ashrrev_i32_e32 v155, 31, v154
	v_readlane_b32 s1, v250, 11
	v_mov_b32_dpp v72, v70 row_shl:4 row_mask:0xf bank_mask:0x5
	v_mov_b32_dpp v72, v70 row_shr:4 row_mask:0xf bank_mask:0xa
	v_mov_b32_dpp v73, v71 row_shl:4 row_mask:0xf bank_mask:0x5
	v_mov_b32_dpp v73, v71 row_shr:4 row_mask:0xf bank_mask:0xa
	v_lshl_add_u64 v[154:155], v[154:155], 2, s[0:1]
	s_nop 1
	v_mov_b32_e32 v184, v190
	v_mov_b32_e32 v180, v194
	v_mov_b32_e32 v185, v191
	v_mov_b32_e32 v181, v195
	v_mov_b32_e32 v186, v192
	v_mov_b32_e32 v182, v196
	v_mov_b32_e32 v187, v193
	v_mov_b32_e32 v183, v197
	v_mov_b32_e32 v155, v186
	v_mov_b32_e32 v186, v185
	s_waitcnt lgkmcnt(0)
	v_pk_mul_f32 v[72:73], v[186:187], v[72:73]
	v_mov_b32_e32 v154, v184
	v_cndmask_b32_e64 v73, v73, -v73, s[42:43]
	v_cndmask_b32_e64 v72, v72, -v72, s[42:43]
	v_pk_fma_f32 v[70:71], v[70:71], v[154:155], v[72:73]
	v_mov_b32_dpp v72, v66 row_shl:4 row_mask:0xf bank_mask:0x5
	v_mov_b32_dpp v72, v66 row_shr:4 row_mask:0xf bank_mask:0xa
	v_mov_b32_dpp v73, v67 row_shl:4 row_mask:0xf bank_mask:0x5
	v_mov_b32_dpp v73, v67 row_shr:4 row_mask:0xf bank_mask:0xa
	v_mov_b32_e32 v155, v182
	v_mov_b32_e32 v182, v181
	v_mov_b32_e32 v154, v180
	s_waitcnt lgkmcnt(0)
	v_pk_mul_f32 v[72:73], v[182:183], v[72:73]
	s_nop 0
	v_cndmask_b32_e64 v73, v73, -v73, s[42:43]
	v_cndmask_b32_e64 v72, v72, -v72, s[42:43]
	v_pk_fma_f32 v[66:67], v[66:67], v[154:155], v[72:73]
.LBB0_648:
	s_mov_b32 s0, 0x3e38aa3b
	v_pk_mul_f32 v[70:71], v[70:71], s[0:1] op_sel_hi:[1,0]
	v_pk_mul_f32 v[66:67], v[66:67], s[0:1] op_sel_hi:[1,0]
	v_lshl_add_u64 v[154:155], s[24:25], 0, v[130:131]
	v_cvt_pk_bf16_f32 v70, v70, v71
	v_cvt_pk_bf16_f32 v71, v66, v67
	v_add_co_u32_e32 v66, vcc, 0x13000000, v154
	s_nop 1
	v_addc_co_u32_e32 v67, vcc, 0, v155, vcc
	global_store_dwordx2 v[66:67], v[70:71], off
	v_lshlrev_b32_e32 v66, 16, v68
	v_and_b32_e32 v67, 0xffff0000, v68
	v_pk_mul_f32 v[180:181], v[66:67], v[66:67]
	v_lshlrev_b32_e32 v68, 16, v69
	v_and_b32_e32 v69, 0xffff0000, v69
	v_pk_mul_f32 v[182:183], v[68:69], v[68:69]
	v_add_f32_e32 v179, v180, v181
	v_add_f32_e32 v179, v182, v179
	v_add_f32_e32 v179, v183, v179
	s_nop 1
	v_mov_b32_dpp v180, v179 quad_perm:[1,0,3,2] row_mask:0xf bank_mask:0xf
	s_waitcnt lgkmcnt(0)
	v_add_f32_e32 v179, v179, v180
	s_nop 1
	v_mov_b32_dpp v180, v179 quad_perm:[2,3,0,1] row_mask:0xf bank_mask:0xf
	s_waitcnt lgkmcnt(0)
	v_add_f32_e32 v179, v179, v180
	s_nop 1
	v_mov_b32_dpp v180, v179 row_shl:4 row_mask:0xf bank_mask:0x5
	v_mov_b32_dpp v180, v179 row_shr:4 row_mask:0xf bank_mask:0xa
	s_waitcnt lgkmcnt(0)
	v_add_f32_e32 v179, v179, v180
	s_nop 1
	v_mov_b32_dpp v180, v179 row_ror:8 row_mask:0xf bank_mask:0xf
	s_waitcnt lgkmcnt(0)
	v_add_f32_e32 v179, v179, v180
	v_fmamk_f32 v179, v179, 0x3c800000, v219
	v_cmp_gt_f32_e32 vcc, s33, v179
	v_mul_f32_e32 v180, 0x4b800000, v179
	s_nop 0
	v_cndmask_b32_e32 v179, v179, v180, vcc
	v_rsq_f32_e32 v179, v179
	s_nop 0
	v_mul_f32_e32 v180, 0x45800000, v179
	v_cndmask_b32_e32 v180, v179, v180, vcc
	v_pk_mul_f32 v[182:183], v[180:181], v[66:67] op_sel_hi:[0,1]
	v_pk_mul_f32 v[180:181], v[180:181], v[68:69] op_sel_hi:[0,1]
	s_and_b64 vcc, exec, s[72:73]
	v_mov_b32_e32 v70, v206
	v_mov_b32_e32 v71, v207
	v_mov_b32_e32 v72, v208
	v_mov_b32_e32 v73, v209
	v_pk_mul_f32 v[70:71], v[70:71], v[182:183]
	v_pk_mul_f32 v[72:73], v[72:73], v[180:181]
	s_cbranch_vccnz .LBB0_650
	v_lshl_or_b32 v178, v178, 5, v159
	v_readlane_b32 s0, v250, 10
	v_ashrrev_i32_e32 v179, 31, v178
	v_readlane_b32 s1, v250, 11
	v_mov_b32_dpp v186, v70 row_shl:4 row_mask:0xf bank_mask:0x5
	v_mov_b32_dpp v186, v70 row_shr:4 row_mask:0xf bank_mask:0xa
	v_mov_b32_dpp v187, v71 row_shl:4 row_mask:0xf bank_mask:0x5
	v_mov_b32_dpp v187, v71 row_shr:4 row_mask:0xf bank_mask:0xa
	v_lshl_add_u64 v[182:183], v[178:179], 2, s[0:1]
	s_nop 1
	v_mov_b32_e32 v182, v190
	v_mov_b32_e32 v178, v194
	v_mov_b32_e32 v183, v191
	v_mov_b32_e32 v179, v195
	v_mov_b32_e32 v184, v192
	v_mov_b32_e32 v180, v196
	v_mov_b32_e32 v185, v193
	v_mov_b32_e32 v181, v197
	v_mov_b32_e32 v189, v184
	v_mov_b32_e32 v184, v183
	v_mov_b32_e32 v188, v182
	s_waitcnt lgkmcnt(0)
	v_pk_mul_f32 v[182:183], v[184:185], v[186:187]
	v_mov_b32_e32 v185, v180
	v_cndmask_b32_e64 v183, v183, -v183, s[42:43]
	v_cndmask_b32_e64 v182, v182, -v182, s[42:43]
	v_pk_fma_f32 v[70:71], v[70:71], v[188:189], v[182:183]
	v_mov_b32_dpp v182, v72 row_shl:4 row_mask:0xf bank_mask:0x5
	v_mov_b32_dpp v182, v72 row_shr:4 row_mask:0xf bank_mask:0xa
	v_mov_b32_dpp v183, v73 row_shl:4 row_mask:0xf bank_mask:0x5
	v_mov_b32_dpp v183, v73 row_shr:4 row_mask:0xf bank_mask:0xa
	v_mov_b32_e32 v180, v179
	v_mov_b32_e32 v184, v178
	s_waitcnt lgkmcnt(0)
	v_pk_mul_f32 v[178:179], v[180:181], v[182:183]
	s_nop 0
	v_cndmask_b32_e64 v179, v179, -v179, s[42:43]
	v_cndmask_b32_e64 v178, v178, -v178, s[42:43]
	v_pk_fma_f32 v[72:73], v[72:73], v[184:185], v[178:179]

.LBB0_656:
	s_or_b64 exec, exec, s[8:9]
	v_lshlrev_b32_e32 v66, 16, v156
	v_and_b32_e32 v67, 0xffff0000, v156
	v_lshlrev_b32_e32 v68, 16, v157
	v_and_b32_e32 v69, 0xffff0000, v157
	s_and_b64 vcc, exec, s[72:73]
	v_cndmask_b32_e64 v156, v176, v177, s[42:43]
	s_cbranch_vccnz .LBB0_658
	v_lshl_or_b32 v70, v156, 4, v160
	v_readlane_b32 s8, v251, 13
	v_ashrrev_i32_e32 v71, 31, v70
	v_readlane_b32 s9, v251, 14
	v_mov_b32_dpp v180, v66 quad_perm:[2,3,0,1] row_mask:0xf bank_mask:0xf
	v_mov_b32_dpp v181, v67 quad_perm:[2,3,0,1] row_mask:0xf bank_mask:0xf
	v_lshl_add_u64 v[176:177], v[70:71], 2, s[8:9]
	s_nop 1
	v_mov_b32_e32 v176, v198
	v_mov_b32_e32 v70, v202
	v_mov_b32_e32 v177, v199
	v_mov_b32_e32 v71, v203
	v_mov_b32_e32 v178, v200
	v_mov_b32_e32 v72, v204
	v_mov_b32_e32 v179, v201
	v_mov_b32_e32 v73, v205
	v_mov_b32_e32 v183, v178
	v_mov_b32_e32 v178, v177
	v_mov_b32_e32 v182, v176
	s_waitcnt lgkmcnt(0)
	v_pk_mul_f32 v[176:177], v[178:179], v[180:181]
	v_mov_b32_e32 v179, v72
	v_cndmask_b32_e64 v177, v177, -v177, s[46:47]
	v_cndmask_b32_e64 v176, v176, -v176, s[46:47]
	v_pk_fma_f32 v[66:67], v[182:183], v[66:67], v[176:177]
	v_mov_b32_dpp v176, v68 quad_perm:[2,3,0,1] row_mask:0xf bank_mask:0xf
	v_mov_b32_dpp v177, v69 quad_perm:[2,3,0,1] row_mask:0xf bank_mask:0xf
	v_mov_b32_e32 v72, v71
	v_mov_b32_e32 v178, v70
	s_waitcnt lgkmcnt(0)
	v_pk_mul_f32 v[70:71], v[72:73], v[176:177]
	s_nop 0
	v_cndmask_b32_e64 v71, v71, -v71, s[46:47]
	v_cndmask_b32_e64 v70, v70, -v70, s[46:47]
	v_pk_fma_f32 v[68:69], v[178:179], v[68:69], v[70:71]
